# GEMM K-rotation offset per 8-WG group = 3 K-steps (was 4): spreads the 8 groups of an XCD over distinct 128B line residues mod 16
# baseline (speedup 1.0000x reference)
.LBB0_261:
	s_ashr_i32 s79, s78, 31
	s_lshl_b64 s[2:3], s[78:79], 12
	s_lshl_b32 s78, s14, 8
	s_mov_b64 s[82:83], -1
	s_and_b64 vcc, exec, s[80:81]
	s_cbranch_vccz .LBB0_287
	v_mov_b32_e32 v10, v156
	s_add_u32 s14, s4, s2
	s_addc_u32 s15, s5, s3
	v_ashrrev_i32_e32 v0, 3, v10
	s_add_i32 s80, s78, 0x400
	v_xor_b32_e32 v6, v0, v10
	v_ashrrev_i32_e32 v1, 31, v0
	s_ashr_i32 s81, s80, 31
	v_lshlrev_b64 v[2:3], 12, v[0:1]
	v_lshlrev_b32_e32 v1, 4, v6
	s_lshl_b64 s[80:81], s[80:81], 12
	v_and_b32_e32 v144, 0x70, v1
	v_lshlrev_b32_e32 v1, 4, v10
	s_add_u32 s82, s70, s80
	v_add_u32_e32 v139, 0, v1
	s_addc_u32 s83, s71, s81
	v_lshl_add_u64 v[4:5], s[14:15], 0, v[2:3]
	v_add_u32_e32 v140, s86, v1
	v_readfirstlane_b32 s14, v139
	v_lshl_add_u64 v[4:5], v[4:5], 0, v[144:145]
	v_lshl_add_u64 v[6:7], s[82:83], 0, v[2:3]
	s_mov_b32 m0, s14
	v_readfirstlane_b32 s14, v140
	v_add_u32_e32 v1, 0x2000, v139
	v_lshl_add_u64 v[6:7], v[6:7], 0, v[144:145]
	s_barrier
	global_load_lds_dwordx4 v[4:5], off
	s_mov_b32 m0, s14
	v_readfirstlane_b32 s14, v1
	v_add_u32_e32 v1, 0x2000, v140
	global_load_lds_dwordx4 v[6:7], off
	v_lshl_add_u64 v[8:9], v[4:5], 0, s[50:51]
	s_mov_b32 m0, s14
	v_readfirstlane_b32 s14, v1
	v_add_u32_e32 v1, 0x4000, v139
	global_load_lds_dwordx4 v[8:9], off
	v_lshl_add_u64 v[8:9], v[6:7], 0, s[50:51]
	s_mov_b32 m0, s14
	v_readfirstlane_b32 s14, v1
	v_add_u32_e32 v1, 0x4000, v140
	global_load_lds_dwordx4 v[8:9], off
	v_lshl_add_u64 v[8:9], v[4:5], 0, s[54:55]
	s_mov_b32 m0, s14
	v_readfirstlane_b32 s14, v1
	v_add_u32_e32 v1, 0x6000, v139
	global_load_lds_dwordx4 v[8:9], off
	v_lshl_add_u64 v[8:9], v[6:7], 0, s[54:55]
	s_mov_b32 m0, s14
	v_readfirstlane_b32 s14, v1
	v_add_u32_e32 v1, 0x6000, v140
	global_load_lds_dwordx4 v[8:9], off
	v_lshl_add_u64 v[4:5], v[4:5], 0, s[56:57]
	s_mov_b32 m0, s14
	v_readfirstlane_b32 s14, v1
	global_load_lds_dwordx4 v[4:5], off
	v_lshl_add_u64 v[4:5], v[6:7], 0, s[56:57]
	s_mov_b32 m0, s14
	v_ashrrev_i32_e32 v1, 1, v10
	global_load_lds_dwordx4 v[4:5], off
	v_and_b32_e32 v133, 15, v10
	v_and_b32_e32 v135, 0xffffffc0, v1
	v_bfe_u32 v132, v10, 6, 1
	v_lshrrev_b32_e32 v11, 4, v10
	v_or_b32_e32 v1, v135, v133
	v_and_b32_e32 v6, 7, v10
	v_bfe_u32 v134, v10, 4, 2
	v_lshlrev_b32_e32 v4, 13, v132
	v_lshlrev_b32_e32 v5, 7, v133
	v_lshl_add_u32 v137, v1, 7, 0
	v_bitop3_b32 v1, v11, v6, 3 bitop3:0x6c
	v_bitop3_b32 v0, v0, 7, v10 bitop3:0x48
	v_add3_u32 v136, s86, v4, v5
	v_lshlrev_b32_e32 v141, 4, v1
	v_bitop3_b32 v1, v134, v6, 4 bitop3:0x36
	v_lshl_add_u64 v[4:5], v[2:3], 0, s[2:3]
	v_lshlrev_b32_e32 v144, 4, v0
	v_lshlrev_b32_e32 v138, 4, v1
	v_lshl_add_u64 v[0:1], v[4:5], 0, v[144:145]
	v_lshl_add_u64 v[128:129], s[72:73], 0, v[0:1]
	v_lshl_add_u64 v[0:1], v[2:3], 0, s[80:81]
	s_waitcnt vmcnt(0)
	v_or_b32_e32 v0, v0, v144
	v_lshl_add_u64 v[130:131], s[72:73], 0, v[0:1]
	v_mov_b32_e32 v0, 0
	s_mov_b32 s14, 0
	s_mov_b64 s[80:81], 0
	v_mov_b32_e32 v1, v0
	v_mov_b32_e32 v2, v0
	v_mov_b32_e32 v3, v0
	v_mov_b32_e32 v4, v0
	v_mov_b32_e32 v5, v0
	v_mov_b32_e32 v6, v0
	v_mov_b32_e32 v7, v0
	v_mov_b32_e32 v8, v0
	v_mov_b32_e32 v9, v0
	v_mov_b32_e32 v10, v0
	v_mov_b32_e32 v11, v0
	v_mov_b32_e32 v12, v0
	v_mov_b32_e32 v13, v0
	v_mov_b32_e32 v14, v0
	v_mov_b32_e32 v15, v0
	v_mov_b32_e32 v16, v0
	v_mov_b32_e32 v17, v0
	v_mov_b32_e32 v18, v0
	v_mov_b32_e32 v19, v0
	v_mov_b32_e32 v20, v0
	v_mov_b32_e32 v21, v0
	v_mov_b32_e32 v22, v0
	v_mov_b32_e32 v23, v0
	v_mov_b32_e32 v24, v0
	v_mov_b32_e32 v25, v0
	v_mov_b32_e32 v26, v0
	v_mov_b32_e32 v27, v0
	v_mov_b32_e32 v28, v0
	v_mov_b32_e32 v29, v0
	v_mov_b32_e32 v30, v0
	v_mov_b32_e32 v31, v0
	v_mov_b32_e32 v32, v0
	v_mov_b32_e32 v33, v0
	v_mov_b32_e32 v34, v0
	v_mov_b32_e32 v35, v0
	v_mov_b32_e32 v36, v0
	v_mov_b32_e32 v37, v0
	v_mov_b32_e32 v38, v0
	v_mov_b32_e32 v39, v0
	v_mov_b32_e32 v40, v0
	v_mov_b32_e32 v41, v0
	v_mov_b32_e32 v42, v0
	v_mov_b32_e32 v43, v0
	v_mov_b32_e32 v44, v0
	v_mov_b32_e32 v45, v0
	v_mov_b32_e32 v46, v0
	v_mov_b32_e32 v47, v0
	v_mov_b32_e32 v48, v0
	v_mov_b32_e32 v49, v0
	v_mov_b32_e32 v50, v0
	v_mov_b32_e32 v51, v0
	v_mov_b32_e32 v52, v0
	v_mov_b32_e32 v53, v0
	v_mov_b32_e32 v54, v0
	v_mov_b32_e32 v55, v0
	v_mov_b32_e32 v56, v0
	v_mov_b32_e32 v57, v0
	v_mov_b32_e32 v58, v0
	v_mov_b32_e32 v59, v0
	v_mov_b32_e32 v60, v0
	v_mov_b32_e32 v61, v0
	v_mov_b32_e32 v62, v0
	v_mov_b32_e32 v63, v0
	v_mov_b32_e32 v64, v0
	v_mov_b32_e32 v65, v0
	v_mov_b32_e32 v66, v0
	v_mov_b32_e32 v67, v0
	v_mov_b32_e32 v68, v0
	v_mov_b32_e32 v69, v0
	v_mov_b32_e32 v70, v0
	v_mov_b32_e32 v71, v0
	v_mov_b32_e32 v72, v0
	v_mov_b32_e32 v73, v0
	v_mov_b32_e32 v74, v0
	v_mov_b32_e32 v75, v0
	v_mov_b32_e32 v76, v0
	v_mov_b32_e32 v77, v0
	v_mov_b32_e32 v78, v0
	v_mov_b32_e32 v79, v0
	v_mov_b32_e32 v80, v0
	v_mov_b32_e32 v81, v0
	v_mov_b32_e32 v82, v0
	v_mov_b32_e32 v83, v0
	v_mov_b32_e32 v84, v0
	v_mov_b32_e32 v85, v0
	v_mov_b32_e32 v86, v0
	v_mov_b32_e32 v87, v0
	v_mov_b32_e32 v88, v0
	v_mov_b32_e32 v89, v0
	v_mov_b32_e32 v90, v0
	v_mov_b32_e32 v91, v0
	v_mov_b32_e32 v92, v0
	v_mov_b32_e32 v93, v0
	v_mov_b32_e32 v94, v0
	v_mov_b32_e32 v95, v0
	v_mov_b32_e32 v96, v0
	v_mov_b32_e32 v97, v0
	v_mov_b32_e32 v98, v0
	v_mov_b32_e32 v99, v0
	v_mov_b32_e32 v100, v0
	v_mov_b32_e32 v101, v0
	v_mov_b32_e32 v102, v0
	v_mov_b32_e32 v103, v0
	v_mov_b32_e32 v104, v0
	v_mov_b32_e32 v105, v0
	v_mov_b32_e32 v106, v0
	v_mov_b32_e32 v107, v0
	v_mov_b32_e32 v108, v0
	v_mov_b32_e32 v109, v0
	v_mov_b32_e32 v110, v0
	v_mov_b32_e32 v111, v0
	v_mov_b32_e32 v112, v0
	v_mov_b32_e32 v113, v0
	v_mov_b32_e32 v114, v0
	v_mov_b32_e32 v115, v0
	v_mov_b32_e32 v116, v0
	v_mov_b32_e32 v117, v0
	v_mov_b32_e32 v118, v0
	v_mov_b32_e32 v119, v0
	v_mov_b32_e32 v120, v0
	v_mov_b32_e32 v121, v0
	v_mov_b32_e32 v122, v0
	v_mov_b32_e32 v123, v0
	v_mov_b32_e32 v124, v0
	v_mov_b32_e32 v125, v0
	v_mov_b32_e32 v126, v0
	v_mov_b32_e32 v127, v0
	s_waitcnt vmcnt(0) lgkmcnt(0)
	s_barrier
	v_readfirstlane_b32 s98, v139
	v_readfirstlane_b32 s99, v140
	s_and_b32 s15, s14, 0x8000
	s_xor_b32 s22, s15, 0x8000
	v_add3_u32 v142, v137, v141, s15
	v_add3_u32 v143, v136, v141, s15
	ds_read_b128 v[174:177], v142
	ds_read_b128 v[178:181], v142 offset:2048
	ds_read_b128 v[182:185], v142 offset:4096
	ds_read_b128 v[186:189], v142 offset:6144
	ds_read_b128 v[158:161], v143
	ds_read_b128 v[162:165], v143 offset:2048
	ds_read_b128 v[166:169], v143 offset:4096
	ds_read_b128 v[170:173], v143 offset:6144
	s_add_i32 s100, s98, s22
	s_add_i32 s101, s99, s22
	s_lshr_b32 s22, s23, 3
	s_and_b32 s22, s22, 7
	s_mul_i32 s22, s22, 0x180
	s_add_i32 vcc_lo, s80, s22
	s_cmp_ge_u32 vcc_lo, 0xf80
	s_cselect_b32 vcc_hi, 0xf80, 0
	s_sub_i32 vcc_lo, vcc_lo, vcc_hi
	s_add_u32 s82, vcc_lo, 0x7870080
	s_addc_u32 s83, 0, 0
	s_add_i32 m0, s100, 0x0
	v_lshl_add_u64 v[146:147], v[128:129], 0, s[82:83]
	global_load_lds_dwordx4 v[146:147], off
	s_add_u32 s82, vcc_lo, s58
	s_addc_u32 s83, 0, s59
	s_add_i32 m0, s101, 0x0
	v_lshl_add_u64 v[146:147], v[130:131], 0, s[82:83]
	global_load_lds_dwordx4 v[146:147], off
	s_add_u32 s82, vcc_lo, 0x78b0080
	s_addc_u32 s83, 0, 0
	s_add_i32 m0, s100, 0x2000
	v_lshl_add_u64 v[146:147], v[128:129], 0, s[82:83]
	global_load_lds_dwordx4 v[146:147], off
	s_add_u32 s82, vcc_lo, s60
	s_addc_u32 s83, 0, s61
	s_add_i32 m0, s101, 0x2000
	v_lshl_add_u64 v[146:147], v[130:131], 0, s[82:83]
	global_load_lds_dwordx4 v[146:147], off
	s_add_u32 s82, vcc_lo, 0x78f0080
	s_addc_u32 s83, 0, 0
	s_add_i32 m0, s100, 0x4000
	v_lshl_add_u64 v[146:147], v[128:129], 0, s[82:83]
	global_load_lds_dwordx4 v[146:147], off
	s_add_u32 s82, vcc_lo, s62
	s_addc_u32 s83, 0, s63
	s_add_i32 m0, s101, 0x4000
	v_lshl_add_u64 v[146:147], v[130:131], 0, s[82:83]
	global_load_lds_dwordx4 v[146:147], off
	s_add_u32 s82, vcc_lo, 0x7930080
	s_addc_u32 s83, 0, 0
	s_add_i32 m0, s100, 0x6000
	v_lshl_add_u64 v[146:147], v[128:129], 0, s[82:83]
	global_load_lds_dwordx4 v[146:147], off
	s_add_u32 s82, vcc_lo, s64
	s_addc_u32 s83, 0, s65
	s_add_i32 m0, s101, 0x6000
	v_lshl_add_u64 v[146:147], v[130:131], 0, s[82:83]
	global_load_lds_dwordx4 v[146:147], off
.LBB0_263:
	s_and_b32 s15, s14, 0x8000
	s_add_i32 s14, s14, 0x8000
	v_add3_u32 v142, v137, v138, s15
	v_add3_u32 v143, v136, v141, s15
	v_add3_u32 v144, v136, v138, s15
	s_waitcnt lgkmcnt(3)
	v_mfma_f32_16x16x32_bf16 v[124:127], v[174:177], v[158:161], v[124:127]
	v_mfma_f32_16x16x32_bf16 v[92:95], v[178:181], v[158:161], v[92:95]
	v_mfma_f32_16x16x32_bf16 v[60:63], v[182:185], v[158:161], v[60:63]
	v_mfma_f32_16x16x32_bf16 v[28:31], v[186:189], v[158:161], v[28:31]
	ds_read_b128 v[158:161], v143 offset:16384
	ds_read_b128 v[190:193], v142
	s_waitcnt lgkmcnt(4)
	v_mfma_f32_16x16x32_bf16 v[120:123], v[174:177], v[162:165], v[120:123]
	v_mfma_f32_16x16x32_bf16 v[88:91], v[178:181], v[162:165], v[88:91]
	v_mfma_f32_16x16x32_bf16 v[56:59], v[182:185], v[162:165], v[56:59]
	v_mfma_f32_16x16x32_bf16 v[24:27], v[186:189], v[162:165], v[24:27]
	ds_read_b128 v[162:165], v143 offset:18432
	ds_read_b128 v[194:197], v142 offset:2048
	s_waitcnt lgkmcnt(5)
	v_mfma_f32_16x16x32_bf16 v[116:119], v[174:177], v[166:169], v[116:119]
	v_mfma_f32_16x16x32_bf16 v[84:87], v[178:181], v[166:169], v[84:87]
	v_mfma_f32_16x16x32_bf16 v[52:55], v[182:185], v[166:169], v[52:55]
	v_mfma_f32_16x16x32_bf16 v[20:23], v[186:189], v[166:169], v[20:23]
	ds_read_b128 v[166:169], v143 offset:20480
	ds_read_b128 v[198:201], v142 offset:4096
	s_waitcnt lgkmcnt(6)
	v_mfma_f32_16x16x32_bf16 v[112:115], v[174:177], v[170:173], v[112:115]
	v_mfma_f32_16x16x32_bf16 v[80:83], v[178:181], v[170:173], v[80:83]
	v_mfma_f32_16x16x32_bf16 v[48:51], v[182:185], v[170:173], v[48:51]
	v_mfma_f32_16x16x32_bf16 v[16:19], v[186:189], v[170:173], v[16:19]
	ds_read_b128 v[170:173], v143 offset:22528
	ds_read_b128 v[150:153], v142 offset:6144
	s_waitcnt lgkmcnt(7)
	v_mfma_f32_16x16x32_bf16 v[108:111], v[174:177], v[158:161], v[108:111]
	v_mfma_f32_16x16x32_bf16 v[76:79], v[178:181], v[158:161], v[76:79]
	v_mfma_f32_16x16x32_bf16 v[44:47], v[182:185], v[158:161], v[44:47]
	v_mfma_f32_16x16x32_bf16 v[12:15], v[186:189], v[158:161], v[12:15]
	ds_read_b128 v[158:161], v144
	s_waitcnt lgkmcnt(6)
	v_mfma_f32_16x16x32_bf16 v[104:107], v[174:177], v[162:165], v[104:107]
	v_mfma_f32_16x16x32_bf16 v[72:75], v[178:181], v[162:165], v[72:75]
	v_mfma_f32_16x16x32_bf16 v[40:43], v[182:185], v[162:165], v[40:43]
	v_mfma_f32_16x16x32_bf16 v[8:11], v[186:189], v[162:165], v[8:11]
	ds_read_b128 v[162:165], v144 offset:2048
	s_waitcnt lgkmcnt(5)
	v_mfma_f32_16x16x32_bf16 v[100:103], v[174:177], v[166:169], v[100:103]
	v_mfma_f32_16x16x32_bf16 v[68:71], v[178:181], v[166:169], v[68:71]
	v_mfma_f32_16x16x32_bf16 v[36:39], v[182:185], v[166:169], v[36:39]
	v_mfma_f32_16x16x32_bf16 v[4:7], v[186:189], v[166:169], v[4:7]
	ds_read_b128 v[166:169], v144 offset:4096
	s_waitcnt lgkmcnt(4)
	v_mfma_f32_16x16x32_bf16 v[96:99], v[174:177], v[170:173], v[96:99]
	v_mfma_f32_16x16x32_bf16 v[64:67], v[178:181], v[170:173], v[64:67]
	v_mfma_f32_16x16x32_bf16 v[32:35], v[182:185], v[170:173], v[32:35]
	v_mfma_f32_16x16x32_bf16 v[0:3], v[186:189], v[170:173], v[0:3]
	ds_read_b128 v[170:173], v144 offset:6144
	s_waitcnt lgkmcnt(3)
	v_mfma_f32_16x16x32_bf16 v[124:127], v[190:193], v[158:161], v[124:127]
	v_mfma_f32_16x16x32_bf16 v[92:95], v[194:197], v[158:161], v[92:95]
	v_mfma_f32_16x16x32_bf16 v[60:63], v[198:201], v[158:161], v[60:63]
	v_mfma_f32_16x16x32_bf16 v[28:31], v[150:153], v[158:161], v[28:31]
	ds_read_b128 v[158:161], v144 offset:16384
	s_waitcnt lgkmcnt(3)
	v_mfma_f32_16x16x32_bf16 v[120:123], v[190:193], v[162:165], v[120:123]
	v_mfma_f32_16x16x32_bf16 v[88:91], v[194:197], v[162:165], v[88:91]
	v_mfma_f32_16x16x32_bf16 v[56:59], v[198:201], v[162:165], v[56:59]
	v_mfma_f32_16x16x32_bf16 v[24:27], v[150:153], v[162:165], v[24:27]
	ds_read_b128 v[162:165], v144 offset:18432
	s_waitcnt lgkmcnt(3)
	v_mfma_f32_16x16x32_bf16 v[116:119], v[190:193], v[166:169], v[116:119]
	v_mfma_f32_16x16x32_bf16 v[84:87], v[194:197], v[166:169], v[84:87]
	v_mfma_f32_16x16x32_bf16 v[52:55], v[198:201], v[166:169], v[52:55]
	v_mfma_f32_16x16x32_bf16 v[20:23], v[150:153], v[166:169], v[20:23]
	ds_read_b128 v[166:169], v144 offset:20480
	s_waitcnt lgkmcnt(3)
	v_mfma_f32_16x16x32_bf16 v[112:115], v[190:193], v[170:173], v[112:115]
	v_mfma_f32_16x16x32_bf16 v[80:83], v[194:197], v[170:173], v[80:83]
	v_mfma_f32_16x16x32_bf16 v[48:51], v[198:201], v[170:173], v[48:51]
	v_mfma_f32_16x16x32_bf16 v[16:19], v[150:153], v[170:173], v[16:19]
	ds_read_b128 v[170:173], v144 offset:22528
	s_waitcnt lgkmcnt(3)
	v_mfma_f32_16x16x32_bf16 v[108:111], v[190:193], v[158:161], v[108:111]
	v_mfma_f32_16x16x32_bf16 v[76:79], v[194:197], v[158:161], v[76:79]
	v_mfma_f32_16x16x32_bf16 v[44:47], v[198:201], v[158:161], v[44:47]
	v_mfma_f32_16x16x32_bf16 v[12:15], v[150:153], v[158:161], v[12:15]
	s_add_u32 s80, s80, 0x80
	s_addc_u32 s81, s81, 0
	s_cmpk_eq_i32 s80, 0xf80
	s_waitcnt vmcnt(0) lgkmcnt(0)
	s_barrier
	s_cbranch_scc1 .Lgemm_263_exit
	s_xor_b32 s22, s15, 0x8000
	v_add3_u32 v142, v137, v141, s22
	v_add3_u32 v143, v136, v141, s22
	ds_read_b128 v[174:177], v142
	ds_read_b128 v[178:181], v142 offset:2048
	ds_read_b128 v[182:185], v142 offset:4096
	ds_read_b128 v[186:189], v142 offset:6144
	ds_read_b128 v[158:161], v143
	s_add_i32 s100, s98, s15
	s_add_i32 s101, s99, s15
	s_lshr_b32 s22, s23, 3
	s_and_b32 s22, s22, 7
	s_mul_i32 s22, s22, 0x180
	s_add_i32 vcc_lo, s80, s22
	s_cmp_ge_u32 vcc_lo, 0xf80
	s_cselect_b32 vcc_hi, 0xf80, 0
	s_sub_i32 vcc_lo, vcc_lo, vcc_hi
	s_add_u32 s82, vcc_lo, 0x7870080
	s_addc_u32 s83, 0, 0
	s_add_i32 m0, s100, 0x0
	v_lshl_add_u64 v[146:147], v[128:129], 0, s[82:83]
	global_load_lds_dwordx4 v[146:147], off
	s_add_u32 s82, vcc_lo, s58
	s_addc_u32 s83, 0, s59
	s_add_i32 m0, s101, 0x0
	v_lshl_add_u64 v[146:147], v[130:131], 0, s[82:83]
	global_load_lds_dwordx4 v[146:147], off
	v_mfma_f32_16x16x32_bf16 v[104:107], v[190:193], v[162:165], v[104:107]
	v_mfma_f32_16x16x32_bf16 v[72:75], v[194:197], v[162:165], v[72:75]
	v_mfma_f32_16x16x32_bf16 v[40:43], v[198:201], v[162:165], v[40:43]
	v_mfma_f32_16x16x32_bf16 v[8:11], v[150:153], v[162:165], v[8:11]
	ds_read_b128 v[162:165], v143 offset:2048
	s_add_u32 s82, vcc_lo, 0x78b0080
	s_addc_u32 s83, 0, 0
	s_add_i32 m0, s100, 0x2000
	v_lshl_add_u64 v[146:147], v[128:129], 0, s[82:83]
	global_load_lds_dwordx4 v[146:147], off
	s_add_u32 s82, vcc_lo, s60
	s_addc_u32 s83, 0, s61
	s_add_i32 m0, s101, 0x2000
	v_lshl_add_u64 v[146:147], v[130:131], 0, s[82:83]
	global_load_lds_dwordx4 v[146:147], off
	v_mfma_f32_16x16x32_bf16 v[100:103], v[190:193], v[166:169], v[100:103]
	v_mfma_f32_16x16x32_bf16 v[68:71], v[194:197], v[166:169], v[68:71]
	v_mfma_f32_16x16x32_bf16 v[36:39], v[198:201], v[166:169], v[36:39]
	v_mfma_f32_16x16x32_bf16 v[4:7], v[150:153], v[166:169], v[4:7]
	ds_read_b128 v[166:169], v143 offset:4096
	s_add_u32 s82, vcc_lo, 0x78f0080
	s_addc_u32 s83, 0, 0
	s_add_i32 m0, s100, 0x4000
	v_lshl_add_u64 v[146:147], v[128:129], 0, s[82:83]
	global_load_lds_dwordx4 v[146:147], off
	s_add_u32 s82, vcc_lo, s62
	s_addc_u32 s83, 0, s63
	s_add_i32 m0, s101, 0x4000
	v_lshl_add_u64 v[146:147], v[130:131], 0, s[82:83]
	global_load_lds_dwordx4 v[146:147], off
	v_mfma_f32_16x16x32_bf16 v[96:99], v[190:193], v[170:173], v[96:99]
	v_mfma_f32_16x16x32_bf16 v[64:67], v[194:197], v[170:173], v[64:67]
	v_mfma_f32_16x16x32_bf16 v[32:35], v[198:201], v[170:173], v[32:35]
	v_mfma_f32_16x16x32_bf16 v[0:3], v[150:153], v[170:173], v[0:3]
	ds_read_b128 v[170:173], v143 offset:6144
	s_add_u32 s82, vcc_lo, 0x7930080
	s_addc_u32 s83, 0, 0
	s_add_i32 m0, s100, 0x6000
	v_lshl_add_u64 v[146:147], v[128:129], 0, s[82:83]
	global_load_lds_dwordx4 v[146:147], off
	s_add_u32 s82, vcc_lo, s64
	s_addc_u32 s83, 0, s65
	s_add_i32 m0, s101, 0x6000
	v_lshl_add_u64 v[146:147], v[130:131], 0, s[82:83]
	global_load_lds_dwordx4 v[146:147], off
	s_branch .LBB0_263

.LBB0_620:
	s_ashr_i32 s61, s85, 6
	v_mov_b32_e32 v10, v156
	s_and_b32 s62, s84, 63
	s_and_b32 s63, s85, 63
	s_lshl_b32 s58, s61, 8
	s_lshl_b32 s0, s62, 20
	v_ashrrev_i32_e32 v0, 3, v10
	s_ashr_i32 s59, s58, 31
	s_lshl_b32 s4, s63, 20
	v_xor_b32_e32 v6, v0, v10
	v_ashrrev_i32_e32 v1, 31, v0
	s_add_u32 s4, s24, s4
	v_lshlrev_b64 v[2:3], 12, v[0:1]
	v_lshlrev_b32_e32 v1, 4, v6
	s_addc_u32 s5, s25, 0
	s_lshl_b64 s[64:65], s[58:59], 12
	v_and_b32_e32 v132, 0x70, v1
	v_lshlrev_b32_e32 v1, 4, v10
	s_add_u32 s66, s16, s64
	v_add_u32_e32 v141, 0, v1
	s_addc_u32 s67, s17, s65
	v_lshl_add_u64 v[4:5], s[4:5], 0, v[2:3]
	v_add_u32_e32 v142, s8, v1
	v_readfirstlane_b32 s4, v141
	v_lshl_add_u64 v[4:5], v[4:5], 0, v[132:133]
	v_lshl_add_u64 v[6:7], s[66:67], 0, v[2:3]
	s_mov_b32 m0, s4
	v_readfirstlane_b32 s4, v142
	v_add_u32_e32 v1, 0x2000, v141
	v_lshl_add_u64 v[6:7], v[6:7], 0, v[132:133]
	s_barrier
	global_load_lds_dwordx4 v[4:5], off
	s_mov_b32 m0, s4
	v_readfirstlane_b32 s4, v1
	v_add_u32_e32 v1, 0x2000, v142
	global_load_lds_dwordx4 v[6:7], off
	v_lshl_add_u64 v[8:9], v[4:5], 0, s[6:7]
	s_mov_b32 m0, s4
	v_readfirstlane_b32 s4, v1
	v_add_u32_e32 v1, 0x4000, v141
	global_load_lds_dwordx4 v[8:9], off
	v_lshl_add_u64 v[8:9], v[6:7], 0, s[6:7]
	s_mov_b32 m0, s4
	v_readfirstlane_b32 s4, v1
	v_add_u32_e32 v1, 0x4000, v142
	global_load_lds_dwordx4 v[8:9], off
	v_lshl_add_u64 v[8:9], v[4:5], 0, s[18:19]
	s_mov_b32 m0, s4
	v_readfirstlane_b32 s4, v1
	v_add_u32_e32 v1, 0x6000, v141
	global_load_lds_dwordx4 v[8:9], off
	v_lshl_add_u64 v[8:9], v[6:7], 0, s[18:19]
	s_mov_b32 m0, s4
	v_readfirstlane_b32 s4, v1
	v_add_u32_e32 v1, 0x6000, v142
	global_load_lds_dwordx4 v[8:9], off
	v_lshl_add_u64 v[4:5], v[4:5], 0, s[26:27]
	s_mov_b32 m0, s4
	v_readfirstlane_b32 s4, v1
	global_load_lds_dwordx4 v[4:5], off
	v_lshl_add_u64 v[4:5], v[6:7], 0, s[26:27]
	s_mov_b32 m0, s4
	v_ashrrev_i32_e32 v1, 1, v10
	global_load_lds_dwordx4 v[4:5], off
	v_and_b32_e32 v135, 15, v10
	v_and_b32_e32 v136, 0xffffffc0, v1
	v_lshrrev_b32_e32 v11, 4, v10
	v_or_b32_e32 v1, v136, v135
	v_and_b32_e32 v6, 7, v10
	v_bfe_u32 v134, v10, 6, 1
	v_bfe_u32 v132, v10, 4, 2
	v_lshl_add_u32 v137, v1, 7, 0
	v_bitop3_b32 v1, v11, v6, 3 bitop3:0x6c
	v_lshlrev_b32_e32 v4, 13, v134
	v_lshlrev_b32_e32 v5, 7, v135
	v_lshlrev_b32_e32 v140, 4, v1
	v_bitop3_b32 v1, v132, v6, 4 bitop3:0x36
	v_bitop3_b32 v0, v0, 7, v10 bitop3:0x48
	s_waitcnt vmcnt(0)
	v_add3_u32 v139, s8, v4, v5
	v_lshlrev_b32_e32 v138, 4, v1
	v_lshl_add_u64 v[4:5], s[0:1], 0, v[2:3]
	v_lshlrev_b32_e32 v6, 4, v0
	v_lshl_add_u64 v[0:1], v[2:3], 0, s[64:65]
	v_or_b32_e32 v4, v4, v6
	v_or_b32_e32 v0, v0, v6
	v_lshl_add_u64 v[128:129], s[72:73], 0, v[4:5]
	v_lshl_add_u64 v[130:131], s[72:73], 0, v[0:1]
	s_mov_b64 s[4:5], 0
	s_mov_b32 s60, s1
	v_mov_b32_e32 v20, 0
	v_mov_b32_e32 v21, v133
	v_mov_b32_e32 v22, v133
	v_mov_b32_e32 v23, v133
	v_mov_b32_e32 v56, 0
	v_mov_b32_e32 v57, v133
	v_mov_b32_e32 v58, v133
	v_mov_b32_e32 v59, v133
	v_mov_b32_e32 v0, 0
	v_mov_b32_e32 v1, v133
	v_mov_b32_e32 v2, v133
	v_mov_b32_e32 v3, v133
	v_mov_b32_e32 v32, 0
	v_mov_b32_e32 v33, v133
	v_mov_b32_e32 v34, v133
	v_mov_b32_e32 v35, v133
	v_mov_b32_e32 v64, 0
	v_mov_b32_e32 v65, v133
	v_mov_b32_e32 v66, v133
	v_mov_b32_e32 v67, v133
	v_mov_b32_e32 v68, 0
	v_mov_b32_e32 v69, v133
	v_mov_b32_e32 v70, v133
	v_mov_b32_e32 v71, v133
	v_mov_b32_e32 v72, 0
	v_mov_b32_e32 v73, v133
	v_mov_b32_e32 v74, v133
	v_mov_b32_e32 v75, v133
	v_mov_b32_e32 v76, 0
	v_mov_b32_e32 v77, v133
	v_mov_b32_e32 v78, v133
	v_mov_b32_e32 v79, v133
	v_mov_b32_e32 v4, 0
	v_mov_b32_e32 v5, v133
	v_mov_b32_e32 v6, v133
	v_mov_b32_e32 v7, v133
	v_mov_b32_e32 v36, 0
	v_mov_b32_e32 v37, v133
	v_mov_b32_e32 v38, v133
	v_mov_b32_e32 v39, v133
	v_mov_b32_e32 v8, 0
	v_mov_b32_e32 v9, v133
	v_mov_b32_e32 v10, v133
	v_mov_b32_e32 v11, v133
	v_mov_b32_e32 v40, 0
	v_mov_b32_e32 v41, v133
	v_mov_b32_e32 v42, v133
	v_mov_b32_e32 v43, v133
	v_mov_b32_e32 v80, 0
	v_mov_b32_e32 v81, v133
	v_mov_b32_e32 v82, v133
	v_mov_b32_e32 v83, v133
	v_mov_b32_e32 v84, 0
	v_mov_b32_e32 v85, v133
	v_mov_b32_e32 v86, v133
	v_mov_b32_e32 v87, v133
	v_mov_b32_e32 v88, 0
	v_mov_b32_e32 v89, v133
	v_mov_b32_e32 v90, v133
	v_mov_b32_e32 v91, v133
	v_mov_b32_e32 v92, 0
	v_mov_b32_e32 v93, v133
	v_mov_b32_e32 v94, v133
	v_mov_b32_e32 v95, v133
	v_mov_b32_e32 v12, 0
	v_mov_b32_e32 v13, v133
	v_mov_b32_e32 v14, v133
	v_mov_b32_e32 v15, v133
	v_mov_b32_e32 v44, 0
	v_mov_b32_e32 v45, v133
	v_mov_b32_e32 v46, v133
	v_mov_b32_e32 v47, v133
	v_mov_b32_e32 v16, 0
	v_mov_b32_e32 v17, v133
	v_mov_b32_e32 v18, v133
	v_mov_b32_e32 v19, v133
	v_mov_b32_e32 v48, 0
	v_mov_b32_e32 v49, v133
	v_mov_b32_e32 v50, v133
	v_mov_b32_e32 v51, v133
	v_mov_b32_e32 v96, 0
	v_mov_b32_e32 v97, v133
	v_mov_b32_e32 v98, v133
	v_mov_b32_e32 v99, v133
	v_mov_b32_e32 v100, 0
	v_mov_b32_e32 v101, v133
	v_mov_b32_e32 v102, v133
	v_mov_b32_e32 v103, v133
	v_mov_b32_e32 v104, 0
	v_mov_b32_e32 v105, v133
	v_mov_b32_e32 v106, v133
	v_mov_b32_e32 v107, v133
	v_mov_b32_e32 v108, 0
	v_mov_b32_e32 v109, v133
	v_mov_b32_e32 v110, v133
	v_mov_b32_e32 v111, v133
	v_mov_b32_e32 v24, 0
	v_mov_b32_e32 v25, v133
	v_mov_b32_e32 v26, v133
	v_mov_b32_e32 v27, v133
	v_mov_b32_e32 v52, 0
	v_mov_b32_e32 v53, v133
	v_mov_b32_e32 v54, v133
	v_mov_b32_e32 v55, v133
	v_mov_b32_e32 v28, 0
	v_mov_b32_e32 v29, v133
	v_mov_b32_e32 v30, v133
	v_mov_b32_e32 v31, v133
	v_mov_b32_e32 v60, 0
	v_mov_b32_e32 v61, v133
	v_mov_b32_e32 v62, v133
	v_mov_b32_e32 v63, v133
	v_mov_b32_e32 v112, 0
	v_mov_b32_e32 v113, v133
	v_mov_b32_e32 v114, v133
	v_mov_b32_e32 v115, v133
	v_mov_b32_e32 v116, 0
	v_mov_b32_e32 v117, v133
	v_mov_b32_e32 v118, v133
	v_mov_b32_e32 v119, v133
	v_mov_b32_e32 v120, 0
	v_mov_b32_e32 v121, v133
	v_mov_b32_e32 v122, v133
	v_mov_b32_e32 v123, v133
	v_mov_b32_e32 v124, 0
	v_mov_b32_e32 v125, v133
	v_mov_b32_e32 v126, v133
	v_mov_b32_e32 v127, v133
	s_waitcnt vmcnt(0) lgkmcnt(0)
	s_barrier
	v_readfirstlane_b32 s64, v141
	v_readfirstlane_b32 s65, v142
	s_and_b32 s68, s60, 0x8000
	s_xor_b32 s69, s68, 0x8000
	v_add3_u32 v143, v137, v140, s68
	v_add3_u32 v157, v139, v140, s68
	ds_read_b128 v[174:177], v143
	ds_read_b128 v[178:181], v143 offset:2048
	ds_read_b128 v[182:185], v143 offset:4096
	ds_read_b128 v[144:147], v143 offset:6144
	ds_read_b128 v[158:161], v157
	ds_read_b128 v[162:165], v157 offset:2048
	ds_read_b128 v[166:169], v157 offset:4096
	ds_read_b128 v[170:173], v157 offset:6144
	s_add_i32 s70, s64, s69
	s_add_i32 s71, s65, s69
	s_lshr_b32 s69, s23, 3
	s_and_b32 s69, s69, 7
	s_mul_i32 s69, s69, 0x180
	s_add_i32 vcc_lo, s4, s69
	s_cmp_ge_u32 vcc_lo, 0xf80
	s_cselect_b32 vcc_hi, 0xf80, 0
	s_sub_i32 vcc_lo, vcc_lo, vcc_hi
	s_add_u32 s66, vcc_lo, s36
	s_addc_u32 s67, 0, s37
	s_add_i32 m0, s70, 0x0
	v_lshl_add_u64 v[242:243], v[128:129], 0, s[66:67]
	global_load_lds_dwordx4 v[242:243], off
	s_add_u32 s66, vcc_lo, s38
	s_addc_u32 s67, 0, s39
	s_add_i32 m0, s71, 0x0
	v_lshl_add_u64 v[242:243], v[130:131], 0, s[66:67]
	global_load_lds_dwordx4 v[242:243], off
	s_add_u32 s66, vcc_lo, s40
	s_addc_u32 s67, 0, s41
	s_add_i32 m0, s70, 0x2000
	v_lshl_add_u64 v[242:243], v[128:129], 0, s[66:67]
	global_load_lds_dwordx4 v[242:243], off
	s_add_u32 s66, vcc_lo, s42
	s_addc_u32 s67, 0, s43
	s_add_i32 m0, s71, 0x2000
	v_lshl_add_u64 v[242:243], v[130:131], 0, s[66:67]
	global_load_lds_dwordx4 v[242:243], off
	s_add_u32 s66, vcc_lo, s44
	s_addc_u32 s67, 0, s45
	s_add_i32 m0, s70, 0x4000
	v_lshl_add_u64 v[242:243], v[128:129], 0, s[66:67]
	global_load_lds_dwordx4 v[242:243], off
	s_add_u32 s66, vcc_lo, s48
	s_addc_u32 s67, 0, s49
	s_add_i32 m0, s71, 0x4000
	v_lshl_add_u64 v[242:243], v[130:131], 0, s[66:67]
	global_load_lds_dwordx4 v[242:243], off
	s_add_u32 s66, vcc_lo, s50
	s_addc_u32 s67, 0, s51
	s_add_i32 m0, s70, 0x6000
	v_lshl_add_u64 v[242:243], v[128:129], 0, s[66:67]
	global_load_lds_dwordx4 v[242:243], off
	s_add_u32 s66, vcc_lo, s54
	s_addc_u32 s67, 0, s55
	s_add_i32 m0, s71, 0x6000
	v_lshl_add_u64 v[242:243], v[130:131], 0, s[66:67]
	global_load_lds_dwordx4 v[242:243], off
.LBB0_621:
	s_and_b32 s68, s60, 0x8000
	s_add_i32 s60, s60, 0x8000
	v_add3_u32 v143, v137, v138, s68
	v_add3_u32 v157, v139, v140, s68
	v_add3_u32 v186, v139, v138, s68
	s_waitcnt lgkmcnt(3)
	v_mfma_f32_16x16x32_bf16 v[124:127], v[174:177], v[158:161], v[124:127]
	v_mfma_f32_16x16x32_bf16 v[108:111], v[178:181], v[158:161], v[108:111]
	v_mfma_f32_16x16x32_bf16 v[92:95], v[182:185], v[158:161], v[92:95]
	v_mfma_f32_16x16x32_bf16 v[76:79], v[144:147], v[158:161], v[76:79]
	ds_read_b128 v[158:161], v157 offset:16384
	ds_read_b128 v[148:151], v143
	s_waitcnt lgkmcnt(4)
	v_mfma_f32_16x16x32_bf16 v[120:123], v[174:177], v[162:165], v[120:123]
	v_mfma_f32_16x16x32_bf16 v[104:107], v[178:181], v[162:165], v[104:107]
	v_mfma_f32_16x16x32_bf16 v[88:91], v[182:185], v[162:165], v[88:91]
	v_mfma_f32_16x16x32_bf16 v[72:75], v[144:147], v[162:165], v[72:75]
	ds_read_b128 v[162:165], v157 offset:18432
	ds_read_b128 v[152:155], v143 offset:2048
	s_waitcnt lgkmcnt(5)
	v_mfma_f32_16x16x32_bf16 v[116:119], v[174:177], v[166:169], v[116:119]
	v_mfma_f32_16x16x32_bf16 v[100:103], v[178:181], v[166:169], v[100:103]
	v_mfma_f32_16x16x32_bf16 v[84:87], v[182:185], v[166:169], v[84:87]
	v_mfma_f32_16x16x32_bf16 v[68:71], v[144:147], v[166:169], v[68:71]
	ds_read_b128 v[166:169], v157 offset:20480
	ds_read_b128 v[244:247], v143 offset:4096
	s_waitcnt lgkmcnt(6)
	v_mfma_f32_16x16x32_bf16 v[112:115], v[174:177], v[170:173], v[112:115]
	v_mfma_f32_16x16x32_bf16 v[96:99], v[178:181], v[170:173], v[96:99]
	v_mfma_f32_16x16x32_bf16 v[80:83], v[182:185], v[170:173], v[80:83]
	v_mfma_f32_16x16x32_bf16 v[64:67], v[144:147], v[170:173], v[64:67]
	ds_read_b128 v[170:173], v157 offset:22528
	ds_read_b128 v[248:251], v143 offset:6144
	s_waitcnt lgkmcnt(7)
	v_mfma_f32_16x16x32_bf16 v[60:63], v[174:177], v[158:161], v[60:63]
	v_mfma_f32_16x16x32_bf16 v[48:51], v[178:181], v[158:161], v[48:51]
	v_mfma_f32_16x16x32_bf16 v[40:43], v[182:185], v[158:161], v[40:43]
	v_mfma_f32_16x16x32_bf16 v[32:35], v[144:147], v[158:161], v[32:35]
	ds_read_b128 v[158:161], v186
	s_waitcnt lgkmcnt(6)
	v_mfma_f32_16x16x32_bf16 v[28:31], v[174:177], v[162:165], v[28:31]
	v_mfma_f32_16x16x32_bf16 v[16:19], v[178:181], v[162:165], v[16:19]
	v_mfma_f32_16x16x32_bf16 v[8:11], v[182:185], v[162:165], v[8:11]
	v_mfma_f32_16x16x32_bf16 v[0:3], v[144:147], v[162:165], v[0:3]
	ds_read_b128 v[162:165], v186 offset:2048
	s_waitcnt lgkmcnt(5)
	v_mfma_f32_16x16x32_bf16 v[52:55], v[174:177], v[166:169], v[52:55]
	v_mfma_f32_16x16x32_bf16 v[44:47], v[178:181], v[166:169], v[44:47]
	v_mfma_f32_16x16x32_bf16 v[36:39], v[182:185], v[166:169], v[36:39]
	v_mfma_f32_16x16x32_bf16 v[56:59], v[144:147], v[166:169], v[56:59]
	ds_read_b128 v[166:169], v186 offset:4096
	s_waitcnt lgkmcnt(4)
	v_mfma_f32_16x16x32_bf16 v[24:27], v[174:177], v[170:173], v[24:27]
	v_mfma_f32_16x16x32_bf16 v[12:15], v[178:181], v[170:173], v[12:15]
	v_mfma_f32_16x16x32_bf16 v[4:7], v[182:185], v[170:173], v[4:7]
	v_mfma_f32_16x16x32_bf16 v[20:23], v[144:147], v[170:173], v[20:23]
	ds_read_b128 v[170:173], v186 offset:6144
	s_waitcnt lgkmcnt(3)
	v_mfma_f32_16x16x32_bf16 v[124:127], v[148:151], v[158:161], v[124:127]
	v_mfma_f32_16x16x32_bf16 v[108:111], v[152:155], v[158:161], v[108:111]
	v_mfma_f32_16x16x32_bf16 v[92:95], v[244:247], v[158:161], v[92:95]
	v_mfma_f32_16x16x32_bf16 v[76:79], v[248:251], v[158:161], v[76:79]
	ds_read_b128 v[158:161], v186 offset:16384
	s_waitcnt lgkmcnt(3)
	v_mfma_f32_16x16x32_bf16 v[120:123], v[148:151], v[162:165], v[120:123]
	v_mfma_f32_16x16x32_bf16 v[104:107], v[152:155], v[162:165], v[104:107]
	v_mfma_f32_16x16x32_bf16 v[88:91], v[244:247], v[162:165], v[88:91]
	v_mfma_f32_16x16x32_bf16 v[72:75], v[248:251], v[162:165], v[72:75]
	ds_read_b128 v[162:165], v186 offset:18432
	s_waitcnt lgkmcnt(3)
	v_mfma_f32_16x16x32_bf16 v[116:119], v[148:151], v[166:169], v[116:119]
	v_mfma_f32_16x16x32_bf16 v[100:103], v[152:155], v[166:169], v[100:103]
	v_mfma_f32_16x16x32_bf16 v[84:87], v[244:247], v[166:169], v[84:87]
	v_mfma_f32_16x16x32_bf16 v[68:71], v[248:251], v[166:169], v[68:71]
	ds_read_b128 v[166:169], v186 offset:20480
	s_waitcnt lgkmcnt(3)
	v_mfma_f32_16x16x32_bf16 v[112:115], v[148:151], v[170:173], v[112:115]
	v_mfma_f32_16x16x32_bf16 v[96:99], v[152:155], v[170:173], v[96:99]
	v_mfma_f32_16x16x32_bf16 v[80:83], v[244:247], v[170:173], v[80:83]
	v_mfma_f32_16x16x32_bf16 v[64:67], v[248:251], v[170:173], v[64:67]
	ds_read_b128 v[170:173], v186 offset:22528
	s_waitcnt lgkmcnt(3)
	v_mfma_f32_16x16x32_bf16 v[60:63], v[148:151], v[158:161], v[60:63]
	v_mfma_f32_16x16x32_bf16 v[48:51], v[152:155], v[158:161], v[48:51]
	v_mfma_f32_16x16x32_bf16 v[40:43], v[244:247], v[158:161], v[40:43]
	v_mfma_f32_16x16x32_bf16 v[32:35], v[248:251], v[158:161], v[32:35]
	s_add_u32 s4, s4, 0x80
	s_addc_u32 s5, s5, 0
	s_cmpk_eq_i32 s4, 0xf80
	s_waitcnt vmcnt(0) lgkmcnt(0)
	s_barrier
	s_cbranch_scc1 .Lgemm_621_exit
	s_xor_b32 s69, s68, 0x8000
	v_add3_u32 v143, v137, v140, s69
	v_add3_u32 v157, v139, v140, s69
	ds_read_b128 v[174:177], v143
	ds_read_b128 v[178:181], v143 offset:2048
	ds_read_b128 v[182:185], v143 offset:4096
	ds_read_b128 v[144:147], v143 offset:6144
	ds_read_b128 v[158:161], v157
	s_add_i32 s70, s64, s68
	s_add_i32 s71, s65, s68
	s_lshr_b32 s69, s23, 3
	s_and_b32 s69, s69, 7
	s_mul_i32 s69, s69, 0x180
	s_add_i32 vcc_lo, s4, s69
	s_cmp_ge_u32 vcc_lo, 0xf80
	s_cselect_b32 vcc_hi, 0xf80, 0
	s_sub_i32 vcc_lo, vcc_lo, vcc_hi
	s_add_u32 s66, vcc_lo, s36
	s_addc_u32 s67, 0, s37
	s_add_i32 m0, s70, 0x0
	v_lshl_add_u64 v[242:243], v[128:129], 0, s[66:67]
	global_load_lds_dwordx4 v[242:243], off
	s_add_u32 s66, vcc_lo, s38
	s_addc_u32 s67, 0, s39
	s_add_i32 m0, s71, 0x0
	v_lshl_add_u64 v[242:243], v[130:131], 0, s[66:67]
	global_load_lds_dwordx4 v[242:243], off
	v_mfma_f32_16x16x32_bf16 v[28:31], v[148:151], v[162:165], v[28:31]
	v_mfma_f32_16x16x32_bf16 v[16:19], v[152:155], v[162:165], v[16:19]
	v_mfma_f32_16x16x32_bf16 v[8:11], v[244:247], v[162:165], v[8:11]
	v_mfma_f32_16x16x32_bf16 v[0:3], v[248:251], v[162:165], v[0:3]
	ds_read_b128 v[162:165], v157 offset:2048
	s_add_u32 s66, vcc_lo, s40
	s_addc_u32 s67, 0, s41
	s_add_i32 m0, s70, 0x2000
	v_lshl_add_u64 v[242:243], v[128:129], 0, s[66:67]
	global_load_lds_dwordx4 v[242:243], off
	s_add_u32 s66, vcc_lo, s42
	s_addc_u32 s67, 0, s43
	s_add_i32 m0, s71, 0x2000
	v_lshl_add_u64 v[242:243], v[130:131], 0, s[66:67]
	global_load_lds_dwordx4 v[242:243], off
	v_mfma_f32_16x16x32_bf16 v[52:55], v[148:151], v[166:169], v[52:55]
	v_mfma_f32_16x16x32_bf16 v[44:47], v[152:155], v[166:169], v[44:47]
	v_mfma_f32_16x16x32_bf16 v[36:39], v[244:247], v[166:169], v[36:39]
	v_mfma_f32_16x16x32_bf16 v[56:59], v[248:251], v[166:169], v[56:59]
	ds_read_b128 v[166:169], v157 offset:4096
	s_add_u32 s66, vcc_lo, s44
	s_addc_u32 s67, 0, s45
	s_add_i32 m0, s70, 0x4000
	v_lshl_add_u64 v[242:243], v[128:129], 0, s[66:67]
	global_load_lds_dwordx4 v[242:243], off
	s_add_u32 s66, vcc_lo, s48
	s_addc_u32 s67, 0, s49
	s_add_i32 m0, s71, 0x4000
	v_lshl_add_u64 v[242:243], v[130:131], 0, s[66:67]
	global_load_lds_dwordx4 v[242:243], off
	v_mfma_f32_16x16x32_bf16 v[24:27], v[148:151], v[170:173], v[24:27]
	v_mfma_f32_16x16x32_bf16 v[12:15], v[152:155], v[170:173], v[12:15]
	v_mfma_f32_16x16x32_bf16 v[4:7], v[244:247], v[170:173], v[4:7]
	v_mfma_f32_16x16x32_bf16 v[20:23], v[248:251], v[170:173], v[20:23]
	ds_read_b128 v[170:173], v157 offset:6144
	s_add_u32 s66, vcc_lo, s50
	s_addc_u32 s67, 0, s51
	s_add_i32 m0, s70, 0x6000
	v_lshl_add_u64 v[242:243], v[128:129], 0, s[66:67]
	global_load_lds_dwordx4 v[242:243], off
	s_add_u32 s66, vcc_lo, s54
	s_addc_u32 s67, 0, s55
	s_add_i32 m0, s71, 0x6000
	v_lshl_add_u64 v[242:243], v[130:131], 0, s[66:67]
	global_load_lds_dwordx4 v[242:243], off
	s_branch .LBB0_621

.LBB0_697:
	s_ashr_i32 s55, s54, 6
	v_mov_b32_e32 v10, v156
	s_and_b32 s2, s33, 63
	s_and_b32 s56, s54, 63
	s_lshl_b32 s50, s55, 8
	s_lshl_b32 s2, s2, 20
	v_ashrrev_i32_e32 v0, 3, v10
	s_ashr_i32 s51, s50, 31
	s_lshl_b32 s52, s56, 20
	v_xor_b32_e32 v6, v0, v10
	v_ashrrev_i32_e32 v1, 31, v0
	s_add_u32 s52, s10, s52
	v_lshlrev_b64 v[2:3], 12, v[0:1]
	v_lshlrev_b32_e32 v1, 4, v6
	s_addc_u32 s53, s11, 0
	s_lshl_b64 s[58:59], s[50:51], 12
	v_and_b32_e32 v128, 0x70, v1
	v_lshlrev_b32_e32 v1, 4, v10
	s_add_u32 s60, s12, s58
	v_add_u32_e32 v141, 0, v1
	s_addc_u32 s61, s13, s59
	v_lshl_add_u64 v[4:5], s[52:53], 0, v[2:3]
	v_add_u32_e32 v142, s8, v1
	v_readfirstlane_b32 s52, v141
	v_lshl_add_u64 v[4:5], v[4:5], 0, v[128:129]
	v_lshl_add_u64 v[6:7], s[60:61], 0, v[2:3]
	s_mov_b32 m0, s52
	v_readfirstlane_b32 s52, v142
	v_add_u32_e32 v1, 0x2000, v141
	v_lshl_add_u64 v[6:7], v[6:7], 0, v[128:129]
	s_barrier
	global_load_lds_dwordx4 v[4:5], off
	s_mov_b32 m0, s52
	v_readfirstlane_b32 s52, v1
	v_add_u32_e32 v1, 0x2000, v142
	global_load_lds_dwordx4 v[6:7], off
	v_lshl_add_u64 v[8:9], v[4:5], 0, s[4:5]
	s_mov_b32 m0, s52
	v_readfirstlane_b32 s52, v1
	v_add_u32_e32 v1, 0x4000, v141
	global_load_lds_dwordx4 v[8:9], off
	v_lshl_add_u64 v[8:9], v[6:7], 0, s[4:5]
	s_mov_b32 m0, s52
	v_readfirstlane_b32 s52, v1
	v_add_u32_e32 v1, 0x4000, v142
	global_load_lds_dwordx4 v[8:9], off
	v_lshl_add_u64 v[8:9], v[4:5], 0, s[16:17]
	s_mov_b32 m0, s52
	v_readfirstlane_b32 s52, v1
	v_add_u32_e32 v1, 0x6000, v141
	global_load_lds_dwordx4 v[8:9], off
	v_lshl_add_u64 v[8:9], v[6:7], 0, s[16:17]
	s_mov_b32 m0, s52
	v_readfirstlane_b32 s52, v1
	v_add_u32_e32 v1, 0x6000, v142
	global_load_lds_dwordx4 v[8:9], off
	v_lshl_add_u64 v[4:5], v[4:5], 0, s[18:19]
	s_mov_b32 m0, s52
	v_readfirstlane_b32 s52, v1
	global_load_lds_dwordx4 v[4:5], off
	v_lshl_add_u64 v[4:5], v[6:7], 0, s[18:19]
	s_mov_b32 m0, s52
	v_ashrrev_i32_e32 v1, 1, v10
	global_load_lds_dwordx4 v[4:5], off
	v_and_b32_e32 v136, 15, v10
	v_and_b32_e32 v137, 0xffffffc0, v1
	v_lshrrev_b32_e32 v11, 4, v10
	v_or_b32_e32 v1, v137, v136
	v_and_b32_e32 v6, 7, v10
	v_bfe_u32 v135, v10, 6, 1
	v_bfe_u32 v128, v10, 4, 2
	v_lshl_add_u32 v138, v1, 7, 0
	v_bitop3_b32 v1, v11, v6, 3 bitop3:0x6c
	v_lshlrev_b32_e32 v4, 13, v135
	v_lshlrev_b32_e32 v5, 7, v136
	v_lshlrev_b32_e32 v143, 4, v1
	v_bitop3_b32 v1, v128, v6, 4 bitop3:0x36
	v_bitop3_b32 v0, v0, 7, v10 bitop3:0x48
	s_waitcnt vmcnt(0)
	v_add3_u32 v140, s8, v4, v5
	v_lshlrev_b32_e32 v139, 4, v1
	v_lshl_add_u64 v[4:5], s[2:3], 0, v[2:3]
	v_lshlrev_b32_e32 v6, 4, v0
	v_lshl_add_u64 v[0:1], v[2:3], 0, s[58:59]
	v_or_b32_e32 v4, v4, v6
	v_or_b32_e32 v0, v0, v6
	v_lshl_add_u64 v[130:131], s[72:73], 0, v[4:5]
	v_lshl_add_u64 v[132:133], s[72:73], 0, v[0:1]
	s_mov_b64 s[52:53], 0
	s_mov_b32 s2, 0
	v_mov_b32_e32 v40, 0
	v_mov_b32_e32 v41, v129
	v_mov_b32_e32 v42, v129
	v_mov_b32_e32 v43, v129
	v_mov_b32_e32 v44, 0
	v_mov_b32_e32 v45, v129
	v_mov_b32_e32 v46, v129
	v_mov_b32_e32 v47, v129
	v_mov_b32_e32 v0, 0
	v_mov_b32_e32 v1, v129
	v_mov_b32_e32 v2, v129
	v_mov_b32_e32 v3, v129
	v_mov_b32_e32 v4, 0
	v_mov_b32_e32 v5, v129
	v_mov_b32_e32 v6, v129
	v_mov_b32_e32 v7, v129
	v_mov_b32_e32 v64, 0
	v_mov_b32_e32 v65, v129
	v_mov_b32_e32 v66, v129
	v_mov_b32_e32 v67, v129
	v_mov_b32_e32 v68, 0
	v_mov_b32_e32 v69, v129
	v_mov_b32_e32 v70, v129
	v_mov_b32_e32 v71, v129
	v_mov_b32_e32 v72, 0
	v_mov_b32_e32 v73, v129
	v_mov_b32_e32 v74, v129
	v_mov_b32_e32 v75, v129
	v_mov_b32_e32 v76, 0
	v_mov_b32_e32 v77, v129
	v_mov_b32_e32 v78, v129
	v_mov_b32_e32 v79, v129
	v_mov_b32_e32 v8, 0
	v_mov_b32_e32 v9, v129
	v_mov_b32_e32 v10, v129
	v_mov_b32_e32 v11, v129
	v_mov_b32_e32 v12, 0
	v_mov_b32_e32 v13, v129
	v_mov_b32_e32 v14, v129
	v_mov_b32_e32 v15, v129
	v_mov_b32_e32 v16, 0
	v_mov_b32_e32 v17, v129
	v_mov_b32_e32 v18, v129
	v_mov_b32_e32 v19, v129
	v_mov_b32_e32 v20, 0
	v_mov_b32_e32 v21, v129
	v_mov_b32_e32 v22, v129
	v_mov_b32_e32 v23, v129
	v_mov_b32_e32 v80, 0
	v_mov_b32_e32 v81, v129
	v_mov_b32_e32 v82, v129
	v_mov_b32_e32 v83, v129
	v_mov_b32_e32 v84, 0
	v_mov_b32_e32 v85, v129
	v_mov_b32_e32 v86, v129
	v_mov_b32_e32 v87, v129
	v_mov_b32_e32 v88, 0
	v_mov_b32_e32 v89, v129
	v_mov_b32_e32 v90, v129
	v_mov_b32_e32 v91, v129
	v_mov_b32_e32 v92, 0
	v_mov_b32_e32 v93, v129
	v_mov_b32_e32 v94, v129
	v_mov_b32_e32 v95, v129
	v_mov_b32_e32 v24, 0
	v_mov_b32_e32 v25, v129
	v_mov_b32_e32 v26, v129
	v_mov_b32_e32 v27, v129
	v_mov_b32_e32 v28, 0
	v_mov_b32_e32 v29, v129
	v_mov_b32_e32 v30, v129
	v_mov_b32_e32 v31, v129
	v_mov_b32_e32 v32, 0
	v_mov_b32_e32 v33, v129
	v_mov_b32_e32 v34, v129
	v_mov_b32_e32 v35, v129
	v_mov_b32_e32 v36, 0
	v_mov_b32_e32 v37, v129
	v_mov_b32_e32 v38, v129
	v_mov_b32_e32 v39, v129
	v_mov_b32_e32 v96, 0
	v_mov_b32_e32 v97, v129
	v_mov_b32_e32 v98, v129
	v_mov_b32_e32 v99, v129
	v_mov_b32_e32 v100, 0
	v_mov_b32_e32 v101, v129
	v_mov_b32_e32 v102, v129
	v_mov_b32_e32 v103, v129
	v_mov_b32_e32 v104, 0
	v_mov_b32_e32 v105, v129
	v_mov_b32_e32 v106, v129
	v_mov_b32_e32 v107, v129
	v_mov_b32_e32 v108, 0
	v_mov_b32_e32 v109, v129
	v_mov_b32_e32 v110, v129
	v_mov_b32_e32 v111, v129
	v_mov_b32_e32 v48, 0
	v_mov_b32_e32 v49, v129
	v_mov_b32_e32 v50, v129
	v_mov_b32_e32 v51, v129
	v_mov_b32_e32 v52, 0
	v_mov_b32_e32 v53, v129
	v_mov_b32_e32 v54, v129
	v_mov_b32_e32 v55, v129
	v_mov_b32_e32 v56, 0
	v_mov_b32_e32 v57, v129
	v_mov_b32_e32 v58, v129
	v_mov_b32_e32 v59, v129
	v_mov_b32_e32 v60, 0
	v_mov_b32_e32 v61, v129
	v_mov_b32_e32 v62, v129
	v_mov_b32_e32 v63, v129
	v_mov_b32_e32 v112, 0
	v_mov_b32_e32 v113, v129
	v_mov_b32_e32 v114, v129
	v_mov_b32_e32 v115, v129
	v_mov_b32_e32 v116, 0
	v_mov_b32_e32 v117, v129
	v_mov_b32_e32 v118, v129
	v_mov_b32_e32 v119, v129
	v_mov_b32_e32 v120, 0
	v_mov_b32_e32 v121, v129
	v_mov_b32_e32 v122, v129
	v_mov_b32_e32 v123, v129
	v_mov_b32_e32 v124, 0
	v_mov_b32_e32 v125, v129
	v_mov_b32_e32 v126, v129
	v_mov_b32_e32 v127, v129
	s_waitcnt vmcnt(0) lgkmcnt(0)
	s_barrier
	v_readfirstlane_b32 s57, v141
	v_readfirstlane_b32 s58, v142
	s_and_b32 s59, s2, 0x8000
	s_xor_b32 s62, s59, 0x8000
	v_add3_u32 v157, v138, v143, s59
	v_add3_u32 v186, v140, v143, s59
	ds_read_b128 v[174:177], v157
	ds_read_b128 v[178:181], v157 offset:2048
	ds_read_b128 v[182:185], v157 offset:4096
	ds_read_b128 v[144:147], v157 offset:6144
	ds_read_b128 v[158:161], v186
	ds_read_b128 v[162:165], v186 offset:2048
	ds_read_b128 v[166:169], v186 offset:4096
	ds_read_b128 v[170:173], v186 offset:6144
	s_add_i32 s63, s57, s62
	s_add_i32 s64, s58, s62
	s_lshr_b32 s62, s23, 3
	s_and_b32 s62, s62, 7
	s_mul_i32 s62, s62, 0x180
	s_add_i32 vcc_lo, s52, s62
	s_cmp_ge_u32 vcc_lo, 0xf80
	s_cselect_b32 vcc_hi, 0xf80, 0
	s_sub_i32 vcc_lo, vcc_lo, vcc_hi
	s_add_u32 s60, vcc_lo, s24
	s_addc_u32 s61, 0, s25
	s_add_i32 m0, s63, 0x0
	v_lshl_add_u64 v[242:243], v[130:131], 0, s[60:61]
	global_load_lds_dwordx4 v[242:243], off
	s_add_u32 s60, vcc_lo, s26
	s_addc_u32 s61, 0, s27
	s_add_i32 m0, s64, 0x0
	v_lshl_add_u64 v[242:243], v[132:133], 0, s[60:61]
	global_load_lds_dwordx4 v[242:243], off
	s_add_u32 s60, vcc_lo, s36
	s_addc_u32 s61, 0, s37
	s_add_i32 m0, s63, 0x2000
	v_lshl_add_u64 v[242:243], v[130:131], 0, s[60:61]
	global_load_lds_dwordx4 v[242:243], off
	s_add_u32 s60, vcc_lo, s38
	s_addc_u32 s61, 0, s39
	s_add_i32 m0, s64, 0x2000
	v_lshl_add_u64 v[242:243], v[132:133], 0, s[60:61]
	global_load_lds_dwordx4 v[242:243], off
	s_add_u32 s60, vcc_lo, s40
	s_addc_u32 s61, 0, s41
	s_add_i32 m0, s63, 0x4000
	v_lshl_add_u64 v[242:243], v[130:131], 0, s[60:61]
	global_load_lds_dwordx4 v[242:243], off
	s_add_u32 s60, vcc_lo, s42
	s_addc_u32 s61, 0, s43
	s_add_i32 m0, s64, 0x4000
	v_lshl_add_u64 v[242:243], v[132:133], 0, s[60:61]
	global_load_lds_dwordx4 v[242:243], off
	s_add_u32 s60, vcc_lo, s44
	s_addc_u32 s61, 0, s45
	s_add_i32 m0, s63, 0x6000
	v_lshl_add_u64 v[242:243], v[130:131], 0, s[60:61]
	global_load_lds_dwordx4 v[242:243], off
	s_add_u32 s60, vcc_lo, s48
	s_addc_u32 s61, 0, s49
	s_add_i32 m0, s64, 0x6000
	v_lshl_add_u64 v[242:243], v[132:133], 0, s[60:61]
	global_load_lds_dwordx4 v[242:243], off
.LBB0_698:
	s_and_b32 s59, s2, 0x8000
	s_add_i32 s2, s2, 0x8000
	v_add3_u32 v157, v138, v139, s59
	v_add3_u32 v186, v140, v143, s59
	v_add3_u32 v187, v140, v139, s59
	s_waitcnt lgkmcnt(3)
	v_mfma_f32_16x16x32_bf16 v[124:127], v[174:177], v[158:161], v[124:127]
	v_mfma_f32_16x16x32_bf16 v[108:111], v[178:181], v[158:161], v[108:111]
	v_mfma_f32_16x16x32_bf16 v[92:95], v[182:185], v[158:161], v[92:95]
	v_mfma_f32_16x16x32_bf16 v[76:79], v[144:147], v[158:161], v[76:79]
	ds_read_b128 v[158:161], v186 offset:16384
	ds_read_b128 v[148:151], v157
	s_waitcnt lgkmcnt(4)
	v_mfma_f32_16x16x32_bf16 v[120:123], v[174:177], v[162:165], v[120:123]
	v_mfma_f32_16x16x32_bf16 v[104:107], v[178:181], v[162:165], v[104:107]
	v_mfma_f32_16x16x32_bf16 v[88:91], v[182:185], v[162:165], v[88:91]
	v_mfma_f32_16x16x32_bf16 v[72:75], v[144:147], v[162:165], v[72:75]
	ds_read_b128 v[162:165], v186 offset:18432
	ds_read_b128 v[152:155], v157 offset:2048
	s_waitcnt lgkmcnt(5)
	v_mfma_f32_16x16x32_bf16 v[116:119], v[174:177], v[166:169], v[116:119]
	v_mfma_f32_16x16x32_bf16 v[100:103], v[178:181], v[166:169], v[100:103]
	v_mfma_f32_16x16x32_bf16 v[84:87], v[182:185], v[166:169], v[84:87]
	v_mfma_f32_16x16x32_bf16 v[68:71], v[144:147], v[166:169], v[68:71]
	ds_read_b128 v[166:169], v186 offset:20480
	ds_read_b128 v[244:247], v157 offset:4096
	s_waitcnt lgkmcnt(6)
	v_mfma_f32_16x16x32_bf16 v[112:115], v[174:177], v[170:173], v[112:115]
	v_mfma_f32_16x16x32_bf16 v[96:99], v[178:181], v[170:173], v[96:99]
	v_mfma_f32_16x16x32_bf16 v[80:83], v[182:185], v[170:173], v[80:83]
	v_mfma_f32_16x16x32_bf16 v[64:67], v[144:147], v[170:173], v[64:67]
	ds_read_b128 v[170:173], v186 offset:22528
	ds_read_b128 v[248:251], v157 offset:6144
	s_waitcnt lgkmcnt(7)
	v_mfma_f32_16x16x32_bf16 v[60:63], v[174:177], v[158:161], v[60:63]
	v_mfma_f32_16x16x32_bf16 v[36:39], v[178:181], v[158:161], v[36:39]
	v_mfma_f32_16x16x32_bf16 v[20:23], v[182:185], v[158:161], v[20:23]
	v_mfma_f32_16x16x32_bf16 v[4:7], v[144:147], v[158:161], v[4:7]
	ds_read_b128 v[158:161], v187
	s_waitcnt lgkmcnt(6)
	v_mfma_f32_16x16x32_bf16 v[56:59], v[174:177], v[162:165], v[56:59]
	v_mfma_f32_16x16x32_bf16 v[32:35], v[178:181], v[162:165], v[32:35]
	v_mfma_f32_16x16x32_bf16 v[16:19], v[182:185], v[162:165], v[16:19]
	v_mfma_f32_16x16x32_bf16 v[0:3], v[144:147], v[162:165], v[0:3]
	ds_read_b128 v[162:165], v187 offset:2048
	s_waitcnt lgkmcnt(5)
	v_mfma_f32_16x16x32_bf16 v[52:55], v[174:177], v[166:169], v[52:55]
	v_mfma_f32_16x16x32_bf16 v[28:31], v[178:181], v[166:169], v[28:31]
	v_mfma_f32_16x16x32_bf16 v[12:15], v[182:185], v[166:169], v[12:15]
	v_mfma_f32_16x16x32_bf16 v[44:47], v[144:147], v[166:169], v[44:47]
	ds_read_b128 v[166:169], v187 offset:4096
	s_waitcnt lgkmcnt(4)
	v_mfma_f32_16x16x32_bf16 v[48:51], v[174:177], v[170:173], v[48:51]
	v_mfma_f32_16x16x32_bf16 v[24:27], v[178:181], v[170:173], v[24:27]
	v_mfma_f32_16x16x32_bf16 v[8:11], v[182:185], v[170:173], v[8:11]
	v_mfma_f32_16x16x32_bf16 v[40:43], v[144:147], v[170:173], v[40:43]
	ds_read_b128 v[170:173], v187 offset:6144
	s_waitcnt lgkmcnt(3)
	v_mfma_f32_16x16x32_bf16 v[124:127], v[148:151], v[158:161], v[124:127]
	v_mfma_f32_16x16x32_bf16 v[108:111], v[152:155], v[158:161], v[108:111]
	v_mfma_f32_16x16x32_bf16 v[92:95], v[244:247], v[158:161], v[92:95]
	v_mfma_f32_16x16x32_bf16 v[76:79], v[248:251], v[158:161], v[76:79]
	ds_read_b128 v[158:161], v187 offset:16384
	s_waitcnt lgkmcnt(3)
	v_mfma_f32_16x16x32_bf16 v[120:123], v[148:151], v[162:165], v[120:123]
	v_mfma_f32_16x16x32_bf16 v[104:107], v[152:155], v[162:165], v[104:107]
	v_mfma_f32_16x16x32_bf16 v[88:91], v[244:247], v[162:165], v[88:91]
	v_mfma_f32_16x16x32_bf16 v[72:75], v[248:251], v[162:165], v[72:75]
	ds_read_b128 v[162:165], v187 offset:18432
	s_waitcnt lgkmcnt(3)
	v_mfma_f32_16x16x32_bf16 v[116:119], v[148:151], v[166:169], v[116:119]
	v_mfma_f32_16x16x32_bf16 v[100:103], v[152:155], v[166:169], v[100:103]
	v_mfma_f32_16x16x32_bf16 v[84:87], v[244:247], v[166:169], v[84:87]
	v_mfma_f32_16x16x32_bf16 v[68:71], v[248:251], v[166:169], v[68:71]
	ds_read_b128 v[166:169], v187 offset:20480
	s_waitcnt lgkmcnt(3)
	v_mfma_f32_16x16x32_bf16 v[112:115], v[148:151], v[170:173], v[112:115]
	v_mfma_f32_16x16x32_bf16 v[96:99], v[152:155], v[170:173], v[96:99]
	v_mfma_f32_16x16x32_bf16 v[80:83], v[244:247], v[170:173], v[80:83]
	v_mfma_f32_16x16x32_bf16 v[64:67], v[248:251], v[170:173], v[64:67]
	ds_read_b128 v[170:173], v187 offset:22528
	s_waitcnt lgkmcnt(3)
	v_mfma_f32_16x16x32_bf16 v[60:63], v[148:151], v[158:161], v[60:63]
	v_mfma_f32_16x16x32_bf16 v[36:39], v[152:155], v[158:161], v[36:39]
	v_mfma_f32_16x16x32_bf16 v[20:23], v[244:247], v[158:161], v[20:23]
	v_mfma_f32_16x16x32_bf16 v[4:7], v[248:251], v[158:161], v[4:7]
	s_add_u32 s52, s52, 0x80
	s_addc_u32 s53, s53, 0
	s_cmpk_eq_i32 s52, 0xf80
	s_waitcnt vmcnt(0) lgkmcnt(0)
	s_barrier
	s_cbranch_scc1 .Lgemm_698_exit
	s_xor_b32 s62, s59, 0x8000
	v_add3_u32 v157, v138, v143, s62
	v_add3_u32 v186, v140, v143, s62
	ds_read_b128 v[174:177], v157
	ds_read_b128 v[178:181], v157 offset:2048
	ds_read_b128 v[182:185], v157 offset:4096
	ds_read_b128 v[144:147], v157 offset:6144
	ds_read_b128 v[158:161], v186
	s_add_i32 s63, s57, s59
	s_add_i32 s64, s58, s59
	s_lshr_b32 s62, s23, 3
	s_and_b32 s62, s62, 7
	s_mul_i32 s62, s62, 0x180
	s_add_i32 vcc_lo, s52, s62
	s_cmp_ge_u32 vcc_lo, 0xf80
	s_cselect_b32 vcc_hi, 0xf80, 0
	s_sub_i32 vcc_lo, vcc_lo, vcc_hi
	s_add_u32 s60, vcc_lo, s24
	s_addc_u32 s61, 0, s25
	s_add_i32 m0, s63, 0x0
	v_lshl_add_u64 v[242:243], v[130:131], 0, s[60:61]
	global_load_lds_dwordx4 v[242:243], off
	s_add_u32 s60, vcc_lo, s26
	s_addc_u32 s61, 0, s27
	s_add_i32 m0, s64, 0x0
	v_lshl_add_u64 v[242:243], v[132:133], 0, s[60:61]
	global_load_lds_dwordx4 v[242:243], off
	v_mfma_f32_16x16x32_bf16 v[56:59], v[148:151], v[162:165], v[56:59]
	v_mfma_f32_16x16x32_bf16 v[32:35], v[152:155], v[162:165], v[32:35]
	v_mfma_f32_16x16x32_bf16 v[16:19], v[244:247], v[162:165], v[16:19]
	v_mfma_f32_16x16x32_bf16 v[0:3], v[248:251], v[162:165], v[0:3]
	ds_read_b128 v[162:165], v186 offset:2048
	s_add_u32 s60, vcc_lo, s36
	s_addc_u32 s61, 0, s37
	s_add_i32 m0, s63, 0x2000
	v_lshl_add_u64 v[242:243], v[130:131], 0, s[60:61]
	global_load_lds_dwordx4 v[242:243], off
	s_add_u32 s60, vcc_lo, s38
	s_addc_u32 s61, 0, s39
	s_add_i32 m0, s64, 0x2000
	v_lshl_add_u64 v[242:243], v[132:133], 0, s[60:61]
	global_load_lds_dwordx4 v[242:243], off
	v_mfma_f32_16x16x32_bf16 v[52:55], v[148:151], v[166:169], v[52:55]
	v_mfma_f32_16x16x32_bf16 v[28:31], v[152:155], v[166:169], v[28:31]
	v_mfma_f32_16x16x32_bf16 v[12:15], v[244:247], v[166:169], v[12:15]
	v_mfma_f32_16x16x32_bf16 v[44:47], v[248:251], v[166:169], v[44:47]
	ds_read_b128 v[166:169], v186 offset:4096
	s_add_u32 s60, vcc_lo, s40
	s_addc_u32 s61, 0, s41
	s_add_i32 m0, s63, 0x4000
	v_lshl_add_u64 v[242:243], v[130:131], 0, s[60:61]
	global_load_lds_dwordx4 v[242:243], off
	s_add_u32 s60, vcc_lo, s42
	s_addc_u32 s61, 0, s43
	s_add_i32 m0, s64, 0x4000
	v_lshl_add_u64 v[242:243], v[132:133], 0, s[60:61]
	global_load_lds_dwordx4 v[242:243], off
	v_mfma_f32_16x16x32_bf16 v[48:51], v[148:151], v[170:173], v[48:51]
	v_mfma_f32_16x16x32_bf16 v[24:27], v[152:155], v[170:173], v[24:27]
	v_mfma_f32_16x16x32_bf16 v[8:11], v[244:247], v[170:173], v[8:11]
	v_mfma_f32_16x16x32_bf16 v[40:43], v[248:251], v[170:173], v[40:43]
	ds_read_b128 v[170:173], v186 offset:6144
	s_add_u32 s60, vcc_lo, s44
	s_addc_u32 s61, 0, s45
	s_add_i32 m0, s63, 0x6000
	v_lshl_add_u64 v[242:243], v[130:131], 0, s[60:61]
	global_load_lds_dwordx4 v[242:243], off
	s_add_u32 s60, vcc_lo, s48
	s_addc_u32 s61, 0, s49
	s_add_i32 m0, s64, 0x6000
	v_lshl_add_u64 v[242:243], v[132:133], 0, s[60:61]
	global_load_lds_dwordx4 v[242:243], off
	s_branch .LBB0_698
